# adds: P7 epilogue cvec/ssq loads issued in the last K-loop iteration ahead of the final stage loads; head waits vmcnt(6)
# speedup vs baseline: 1.0076x; 1.0035x over previous
.LBB0_673:
	s_and_b32 s1, s1, 3
	s_lshl_b32 s7, s0, 13
	s_lshl_b32 s8, s1, 12
	s_add_u32 s53, s88, 0x40000
	s_mov_b64 s[36:37], 0x80
	s_addc_u32 s54, s89, 0
	s_add_i32 m0, s48, 0x18000
	v_lshl_add_u64 v[6:7], v[6:7], 0, s[36:37]
	s_waitcnt vmcnt(2)
	s_barrier
	global_load_lds_dwordx4 v[6:7], off
	v_lshl_add_u64 v[4:5], v[4:5], 0, s[36:37]
	s_add_i32 m0, s48, 0x1a000
	s_add_i32 s55, s48, 0x8000
	s_add_i32 s60, s48, 0xa000
	global_load_lds_dwordx4 v[4:5], off
	v_lshl_add_u64 v[2:3], v[2:3], 0, s[36:37]
	s_mov_b32 m0, s55
	s_add_u32 s4, s16, 0x40080
	global_load_lds_dwordx4 v[2:3], off
	v_lshl_add_u64 v[0:1], v[0:1], 0, s[36:37]
	s_mov_b32 m0, s60
	s_addc_u32 s5, s17, 0
	global_load_lds_dwordx4 v[0:1], off
	s_add_i32 m0, s48, 0x1c000
	v_lshl_add_u64 v[0:1], s[4:5], 0, v[178:179]
	global_load_lds_dwordx4 v[0:1], off
	v_lshl_add_u64 v[0:1], s[4:5], 0, v[182:183]
	s_add_i32 m0, s48, 0x1e000
	v_lshlrev_b32_e32 v5, 2, v254
	global_load_lds_dwordx4 v[0:1], off
	v_bfe_u32 v1, v254, 4, 2
	v_and_b32_e32 v0, 15, v254
	v_lshlrev_b32_e32 v2, 3, v1
	v_lshlrev_b32_e32 v3, 4, v1
	v_lshlrev_b32_e32 v6, 6, v254
	s_movk_i32 s4, 0x3c0
	s_cmpk_lt_u32 s6, 0x100
	v_lshl_or_b32 v200, s0, 6, v0
	v_lshl_or_b32 v4, v0, 6, v3
	v_and_b32_e32 v5, 32, v5
	v_and_or_b32 v3, v6, s4, v3
	s_cselect_b64 s[38:39], -1, 0
	s_lshl_b32 s0, s0, 2
	v_lshl_or_b32 v211, s1, 5, v2
	v_lshlrev_b32_e32 v2, 8, v254
	v_bitop3_b32 v201, s8, v3, v5 bitop3:0xf6
	s_or_b32 s0, s0, s1
	v_and_b32_e32 v2, 0x38000, v2
	v_lshlrev_b32_e32 v3, 11, v10
	s_lshl_b32 s13, s0, 10
	s_add_i32 s63, 0, 0x20000
	v_or3_b32 v2, v8, v2, v3
	s_add_i32 s0, s11, s0
	s_add_i32 s11, s63, s13
	v_add_u32_e32 v184, v2, v9
	v_lshlrev_b32_e32 v2, 4, v11
	v_bitop3_b32 v4, v4, s7, v5 bitop3:0xde
	s_waitcnt vmcnt(6)
	v_cmp_lt_u32_e64 s[4:5], 13, v0
	v_cmp_eq_u32_e64 s[6:7], 0, v0
	v_cmp_lt_u32_e64 s[8:9], 1, v0
	s_lshl_b32 s0, s0, 10
	v_lshl_add_u32 v0, v0, 8, s11
	v_and_b32_e32 v2, 0x78000, v2
	v_lshlrev_b32_e32 v202, 6, v1
	v_add_u32_e32 v1, 0xfffff200, v0
	v_add_u32_e32 v0, 0xfffff400, v0
	s_add_i32 s63, s63, s0
	v_or3_b32 v2, v8, v2, v3
	s_add_i32 s65, 0, 0x10000
	s_add_i32 s66, 0, 0x14000
	s_ashr_i32 s61, s33, 31
	s_ashr_i32 s62, s2, 31
	s_add_i32 s64, s63, s10
	v_mov_b32_e32 v185, v179
	v_add_u32_e32 v186, v2, v9
	v_mov_b32_e32 v187, v179
	v_mov_b64_e32 v[188:189], 0x5ac
	v_mov_b64_e32 v[190:191], 0x5ab
	v_add_u32_e32 v212, s65, v201
	v_add_u32_e32 v213, s66, v201
	v_add_u32_e32 v214, 0, v4
	s_movk_i32 s67, 0x1600
	v_mov_b32_e32 v215, 0x358637bd
	v_add_u32_e32 v216, v1, v202
	v_add_u32_e32 v217, v0, v202
	s_barrier
	s_branch .LBB0_676

.LBB0_685:
	ds_read_b128 v[40:43], v212
	ds_read_b128 v[44:47], v212 offset:1024
	ds_read_b128 v[120:123], v212 offset:2048
	ds_read_b128 v[124:127], v212 offset:3072
	ds_read_b128 v[128:131], v213
	ds_read_b128 v[132:135], v213 offset:1024
	ds_read_b128 v[136:139], v213 offset:2048
	ds_read_b128 v[140:143], v213 offset:3072
	s_add_u32 s16, s0, 0xfffc0080
	s_addc_u32 s17, s1, -1
	s_cmp_eq_u32 s24, 12
	s_cselect_b32 s19, s43, s17
	s_cselect_b32 s18, s42, s16
	s_cselect_b32 s17, s13, s23
	s_cselect_b32 s16, s21, s22
	v_lshl_add_u64 v[226:227], s[0:1], 0, v[184:185]
	s_add_i32 m0, s48, 0xc000
	ds_read_b128 v[160:163], v214
	ds_read_b128 v[164:167], v214 offset:1024
	ds_read_b128 v[168:171], v214 offset:2048
	ds_read_b128 v[172:175], v214 offset:3072
	ds_read_b128 v[192:195], v214 offset:4096
	ds_read_b128 v[196:199], v214 offset:5120
	ds_read_b128 v[218:221], v214 offset:6144
	ds_read_b128 v[222:225], v214 offset:7168
	global_load_lds_dwordx4 v[226:227], off
	v_lshl_add_u64 v[226:227], s[0:1], 0, v[186:187]
	s_add_i32 m0, s48, 0xe000
	s_nop 0
	global_load_lds_dwordx4 v[226:227], off
	s_waitcnt vmcnt(8)
	s_waitcnt lgkmcnt(0)
	s_barrier
	s_setprio 1
	s_waitcnt lgkmcnt(0)
	v_mfma_f32_16x16x32_bf16 v[156:159], v[40:43], v[160:163], v[156:159]
	v_mfma_f32_16x16x32_bf16 v[60:63], v[120:123], v[160:163], v[60:63]
	v_mfma_f32_16x16x32_bf16 v[148:151], v[40:43], v[168:171], v[148:151]
	v_mfma_f32_16x16x32_bf16 v[52:55], v[120:123], v[168:171], v[52:55]
	v_mfma_f32_16x16x32_bf16 v[108:111], v[40:43], v[192:195], v[108:111]
	v_mfma_f32_16x16x32_bf16 v[32:35], v[120:123], v[192:195], v[32:35]
	v_mfma_f32_16x16x32_bf16 v[116:119], v[40:43], v[218:221], v[116:119]
	v_mfma_f32_16x16x32_bf16 v[64:67], v[120:123], v[218:221], v[64:67]
	v_mfma_f32_16x16x32_bf16 v[156:159], v[44:47], v[164:167], v[156:159]
	v_mfma_f32_16x16x32_bf16 v[60:63], v[124:127], v[164:167], v[60:63]
	v_mfma_f32_16x16x32_bf16 v[148:151], v[44:47], v[172:175], v[148:151]
	v_mfma_f32_16x16x32_bf16 v[52:55], v[124:127], v[172:175], v[52:55]
	v_mfma_f32_16x16x32_bf16 v[108:111], v[44:47], v[196:199], v[108:111]
	v_mfma_f32_16x16x32_bf16 v[32:35], v[124:127], v[196:199], v[32:35]
	v_mfma_f32_16x16x32_bf16 v[116:119], v[44:47], v[222:225], v[116:119]
	v_mfma_f32_16x16x32_bf16 v[64:67], v[124:127], v[222:225], v[64:67]
	s_setprio 0
	s_setprio 1
	v_mfma_f32_16x16x32_bf16 v[152:155], v[128:131], v[160:163], v[152:155]
	v_mfma_f32_16x16x32_bf16 v[56:59], v[136:139], v[160:163], v[56:59]
	v_mfma_f32_16x16x32_bf16 v[144:147], v[128:131], v[168:171], v[144:147]
	v_mfma_f32_16x16x32_bf16 v[48:51], v[136:139], v[168:171], v[48:51]
	v_mfma_f32_16x16x32_bf16 v[100:103], v[128:131], v[192:195], v[100:103]
	v_mfma_f32_16x16x32_bf16 v[28:31], v[136:139], v[192:195], v[28:31]
	v_mfma_f32_16x16x32_bf16 v[112:115], v[128:131], v[218:221], v[112:115]
	v_mfma_f32_16x16x32_bf16 v[68:71], v[136:139], v[218:221], v[68:71]
	v_mfma_f32_16x16x32_bf16 v[152:155], v[132:135], v[164:167], v[152:155]
	v_mfma_f32_16x16x32_bf16 v[56:59], v[140:143], v[164:167], v[56:59]
	v_mfma_f32_16x16x32_bf16 v[144:147], v[132:135], v[172:175], v[144:147]
	v_mfma_f32_16x16x32_bf16 v[48:51], v[140:143], v[172:175], v[48:51]
	v_mfma_f32_16x16x32_bf16 v[100:103], v[132:135], v[196:199], v[100:103]
	v_mfma_f32_16x16x32_bf16 v[28:31], v[140:143], v[196:199], v[28:31]
	v_mfma_f32_16x16x32_bf16 v[112:115], v[132:135], v[222:225], v[112:115]
	v_mfma_f32_16x16x32_bf16 v[68:71], v[140:143], v[222:225], v[68:71]
	s_setprio 0
	s_barrier
	s_add_i32 s25, s65, s3
	v_lshl_add_u64 v[226:227], s[16:17], 0, v[178:179]
	s_mov_b32 m0, s25
	ds_read_b128 v[160:163], v214 offset:16384
	ds_read_b128 v[164:167], v214 offset:17408
	ds_read_b128 v[168:171], v214 offset:18432
	ds_read_b128 v[172:175], v214 offset:19456
	ds_read_b128 v[192:195], v214 offset:20480
	ds_read_b128 v[196:199], v214 offset:21504
	ds_read_b128 v[218:221], v214 offset:22528
	ds_read_b128 v[222:225], v214 offset:23552
	global_load_lds_dwordx4 v[226:227], off
	s_add_i32 m0, s25, 0x2000
	s_add_u32 s26, s16, 0x40000
	v_lshl_add_u64 v[228:229], s[16:17], 0, v[182:183]
	s_addc_u32 s27, s17, 0
	s_add_i32 s25, s66, s3
	global_load_lds_dwordx4 v[228:229], off
	v_lshl_add_u64 v[230:231], s[26:27], 0, v[178:179]
	s_mov_b32 m0, s25
	v_lshl_add_u64 v[232:233], s[18:19], 0, v[180:181]
	global_load_lds_dwordx4 v[230:231], off
	v_lshl_add_u64 v[230:231], s[26:27], 0, v[182:183]
	s_add_i32 m0, s25, 0x2000
	s_nop 0
	global_load_lds_dwordx4 v[230:231], off
	v_lshl_add_u64 v[230:231], s[18:19], 0, v[176:177]
	s_mov_b32 m0, s48
	s_nop 0
	global_load_lds_dwordx4 v[230:231], off
	s_mov_b32 m0, s49
	s_nop 0
	global_load_lds_dwordx4 v[232:233], off
	s_waitcnt vmcnt(8)
	s_waitcnt lgkmcnt(0)
	s_barrier
	s_setprio 1
	s_waitcnt lgkmcnt(0)
	v_mfma_f32_16x16x32_bf16 v[92:95], v[40:43], v[160:163], v[92:95]
	v_mfma_f32_16x16x32_bf16 v[20:23], v[120:123], v[160:163], v[20:23]
	v_mfma_f32_16x16x32_bf16 v[84:87], v[40:43], v[168:171], v[84:87]
	v_mfma_f32_16x16x32_bf16 v[12:15], v[120:123], v[168:171], v[12:15]
	v_mfma_f32_16x16x32_bf16 v[76:79], v[40:43], v[192:195], v[76:79]
	v_mfma_f32_16x16x32_bf16 v[4:7], v[120:123], v[192:195], v[4:7]
	v_mfma_f32_16x16x32_bf16 v[24:27], v[120:123], v[218:221], v[24:27]
	v_mfma_f32_16x16x32_bf16 v[92:95], v[44:47], v[164:167], v[92:95]
	v_mfma_f32_16x16x32_bf16 v[20:23], v[124:127], v[164:167], v[20:23]
	v_mfma_f32_16x16x32_bf16 v[84:87], v[44:47], v[172:175], v[84:87]
	v_mfma_f32_16x16x32_bf16 v[12:15], v[124:127], v[172:175], v[12:15]
	v_mfma_f32_16x16x32_bf16 v[76:79], v[44:47], v[196:199], v[76:79]
	v_mfma_f32_16x16x32_bf16 v[4:7], v[124:127], v[196:199], v[4:7]
	v_mfma_f32_16x16x32_bf16 v[40:43], v[40:43], v[218:221], v[96:99]
	v_mfma_f32_16x16x32_bf16 v[24:27], v[124:127], v[222:225], v[24:27]
	v_mfma_f32_16x16x32_bf16 v[40:43], v[44:47], v[222:225], v[40:43]
	s_setprio 0
	s_setprio 1
	v_mfma_f32_16x16x32_bf16 v[44:47], v[128:131], v[160:163], v[88:91]
	v_mfma_f32_16x16x32_bf16 v[16:19], v[136:139], v[160:163], v[16:19]
	v_mfma_f32_16x16x32_bf16 v[80:83], v[128:131], v[168:171], v[80:83]
	v_mfma_f32_16x16x32_bf16 v[8:11], v[136:139], v[168:171], v[8:11]
	v_mfma_f32_16x16x32_bf16 v[72:75], v[128:131], v[192:195], v[72:75]
	v_mfma_f32_16x16x32_bf16 v[0:3], v[136:139], v[192:195], v[0:3]
	v_mfma_f32_16x16x32_bf16 v[88:91], v[128:131], v[218:221], v[104:107]
	v_mfma_f32_16x16x32_bf16 v[36:39], v[136:139], v[218:221], v[36:39]
	v_mfma_f32_16x16x32_bf16 v[16:19], v[140:143], v[164:167], v[16:19]
	v_mfma_f32_16x16x32_bf16 v[80:83], v[132:135], v[172:175], v[80:83]
	v_mfma_f32_16x16x32_bf16 v[8:11], v[140:143], v[172:175], v[8:11]
	v_mfma_f32_16x16x32_bf16 v[72:75], v[132:135], v[196:199], v[72:75]
	v_mfma_f32_16x16x32_bf16 v[0:3], v[140:143], v[196:199], v[0:3]
	v_mfma_f32_16x16x32_bf16 v[104:107], v[132:135], v[222:225], v[88:91]
	v_mfma_f32_16x16x32_bf16 v[36:39], v[140:143], v[222:225], v[36:39]
	v_mfma_f32_16x16x32_bf16 v[44:47], v[132:135], v[164:167], v[44:47]
	s_setprio 0
	s_barrier
	s_add_i32 s25, 0, 0x18000
	s_add_i32 s26, 0, 0x1c000
	v_add_u32_e32 v124, s25, v201
	v_add_u32_e32 v140, s26, v201
	ds_read_b128 v[88:91], v124
	ds_read_b128 v[96:99], v124 offset:1024
	ds_read_b128 v[120:123], v124 offset:2048
	ds_read_b128 v[124:127], v124 offset:3072
	ds_read_b128 v[128:131], v140
	ds_read_b128 v[132:135], v140 offset:1024
	ds_read_b128 v[136:139], v140 offset:2048
	ds_read_b128 v[140:143], v140 offset:3072
	s_add_u32 s18, s18, 0x40000
	s_addc_u32 s19, s19, 0
	s_mov_b32 m0, s50
	v_lshl_add_u64 v[234:235], s[18:19], 0, v[176:177]
	ds_read_b128 v[160:163], v214 offset:32768
	ds_read_b128 v[164:167], v214 offset:33792
	ds_read_b128 v[168:171], v214 offset:34816
	ds_read_b128 v[172:175], v214 offset:35840
	ds_read_b128 v[192:195], v214 offset:36864
	ds_read_b128 v[196:199], v214 offset:37888
	ds_read_b128 v[218:221], v214 offset:38912
	ds_read_b128 v[222:225], v214 offset:39936
	global_load_lds_dwordx4 v[234:235], off
	v_lshl_add_u64 v[234:235], s[18:19], 0, v[180:181]
	s_mov_b32 m0, s51
	s_nop 0
	global_load_lds_dwordx4 v[234:235], off
	s_waitcnt vmcnt(8)
	s_waitcnt lgkmcnt(0)
	s_barrier
	s_setprio 1
	s_waitcnt lgkmcnt(0)
	v_mfma_f32_16x16x32_bf16 v[156:159], v[88:91], v[160:163], v[156:159]
	v_mfma_f32_16x16x32_bf16 v[60:63], v[120:123], v[160:163], v[60:63]
	v_mfma_f32_16x16x32_bf16 v[148:151], v[88:91], v[168:171], v[148:151]
	v_mfma_f32_16x16x32_bf16 v[52:55], v[120:123], v[168:171], v[52:55]
	v_mfma_f32_16x16x32_bf16 v[108:111], v[88:91], v[192:195], v[108:111]
	v_mfma_f32_16x16x32_bf16 v[32:35], v[120:123], v[192:195], v[32:35]
	v_mfma_f32_16x16x32_bf16 v[116:119], v[88:91], v[218:221], v[116:119]
	v_mfma_f32_16x16x32_bf16 v[64:67], v[120:123], v[218:221], v[64:67]
	v_mfma_f32_16x16x32_bf16 v[156:159], v[96:99], v[164:167], v[156:159]
	v_mfma_f32_16x16x32_bf16 v[60:63], v[124:127], v[164:167], v[60:63]
	v_mfma_f32_16x16x32_bf16 v[148:151], v[96:99], v[172:175], v[148:151]
	v_mfma_f32_16x16x32_bf16 v[52:55], v[124:127], v[172:175], v[52:55]
	v_mfma_f32_16x16x32_bf16 v[108:111], v[96:99], v[196:199], v[108:111]
	v_mfma_f32_16x16x32_bf16 v[32:35], v[124:127], v[196:199], v[32:35]
	v_mfma_f32_16x16x32_bf16 v[116:119], v[96:99], v[222:225], v[116:119]
	v_mfma_f32_16x16x32_bf16 v[64:67], v[124:127], v[222:225], v[64:67]
	s_setprio 0
	s_setprio 1
	v_mfma_f32_16x16x32_bf16 v[152:155], v[128:131], v[160:163], v[152:155]
	v_mfma_f32_16x16x32_bf16 v[56:59], v[136:139], v[160:163], v[56:59]
	v_mfma_f32_16x16x32_bf16 v[144:147], v[128:131], v[168:171], v[144:147]
	v_mfma_f32_16x16x32_bf16 v[48:51], v[136:139], v[168:171], v[48:51]
	v_mfma_f32_16x16x32_bf16 v[100:103], v[128:131], v[192:195], v[100:103]
	v_mfma_f32_16x16x32_bf16 v[28:31], v[136:139], v[192:195], v[28:31]
	v_mfma_f32_16x16x32_bf16 v[112:115], v[128:131], v[218:221], v[112:115]
	v_mfma_f32_16x16x32_bf16 v[68:71], v[136:139], v[218:221], v[68:71]
	v_mfma_f32_16x16x32_bf16 v[152:155], v[132:135], v[164:167], v[152:155]
	v_mfma_f32_16x16x32_bf16 v[56:59], v[140:143], v[164:167], v[56:59]
	v_mfma_f32_16x16x32_bf16 v[144:147], v[132:135], v[172:175], v[144:147]
	v_mfma_f32_16x16x32_bf16 v[48:51], v[140:143], v[172:175], v[48:51]
	v_mfma_f32_16x16x32_bf16 v[100:103], v[132:135], v[196:199], v[100:103]
	v_mfma_f32_16x16x32_bf16 v[28:31], v[140:143], v[196:199], v[28:31]
	v_mfma_f32_16x16x32_bf16 v[112:115], v[132:135], v[222:225], v[112:115]
	v_mfma_f32_16x16x32_bf16 v[68:71], v[140:143], v[222:225], v[68:71]
	s_setprio 0
	s_barrier
	s_add_i32 s18, s25, s3
	v_lshl_add_u64 v[226:227], v[226:227], 0, s[36:37]
	s_mov_b32 m0, s18
	ds_read_b128 v[160:163], v214 offset:49152
	ds_read_b128 v[164:167], v214 offset:50176
	ds_read_b128 v[168:171], v214 offset:51200
	ds_read_b128 v[172:175], v214 offset:52224
	ds_read_b128 v[192:195], v214 offset:53248
	ds_read_b128 v[196:199], v214 offset:54272
	ds_read_b128 v[218:221], v214 offset:55296
	ds_read_b128 v[222:225], v214 offset:56320
	s_cmp_lg_u32 s24, 12
	s_cbranch_scc1 .Lp7_nopf
	s_mul_hi_i32 s46, s20, 0x3e0f83e1
	s_lshr_b32 s47, s46, 31
	s_ashr_i32 s46, s46, 3
	s_add_i32 s46, s46, s47
	s_mul_i32 s47, s46, 33
	s_sub_i32 s47, s20, s47
	s_mul_i32 s47, s47, 0xfe
	s_min_i32 s47, s47, 0x1f00
	s_lshl_b32 s41, s46, 13
	s_add_i32 s41, s41, s47
	s_mulk_i32 s46, 0x1600
	s_lshl_b32 s46, s46, 2
	s_add_u32 s46, s53, s46
	s_addc_u32 s47, s54, 0
	v_lshl_or_b32 v209, s12, 8, v211
	v_lshlrev_b32_e32 v209, 2, v209
	v_add_u32_e32 v210, s41, v200
	v_lshlrev_b32_e32 v210, 2, v210
	global_load_dwordx4 v[236:239], v209, s[46:47] offset:16
	global_load_dwordx4 v[240:243], v209, s[46:47]
	global_load_dwordx4 v[246:249], v209, s[46:47] offset:528
	global_load_dwordx4 v[250:253], v209, s[46:47] offset:512
	global_load_dword v244, v210, s[96:97] offset:192
	global_load_dword v245, v210, s[96:97] offset:704
	global_load_dword v208, v210, s[96:97]
	global_load_dword v203, v210, s[96:97] offset:64
	global_load_dword v204, v210, s[96:97] offset:128
	global_load_dword v205, v210, s[96:97] offset:512
	global_load_dword v206, v210, s[96:97] offset:576
	global_load_dword v207, v210, s[96:97] offset:640
.Lp7_nopf:
	global_load_lds_dwordx4 v[226:227], off
	s_add_i32 m0, s18, 0x2000
	s_add_u32 s16, s16, 0x40080
	v_lshl_add_u64 v[226:227], v[228:229], 0, s[36:37]
	s_addc_u32 s17, s17, 0
	s_add_i32 s18, s26, s3
	global_load_lds_dwordx4 v[226:227], off
	v_lshl_add_u64 v[226:227], s[16:17], 0, v[178:179]
	s_mov_b32 m0, s18
	s_nop 0
	global_load_lds_dwordx4 v[226:227], off
	v_lshl_add_u64 v[226:227], s[16:17], 0, v[182:183]
	s_add_i32 m0, s18, 0x2000
	s_nop 0
	global_load_lds_dwordx4 v[226:227], off
	v_lshl_add_u64 v[226:227], v[230:231], 0, s[36:37]
	s_mov_b32 m0, s55
	s_nop 0
	global_load_lds_dwordx4 v[226:227], off
	v_lshl_add_u64 v[226:227], v[232:233], 0, s[36:37]
	s_mov_b32 m0, s60
	s_nop 0
	global_load_lds_dwordx4 v[226:227], off
	s_cmp_lg_u32 s24, 12
	s_cbranch_scc1 .Lp7_w8
	s_waitcnt vmcnt(20)
	s_branch .Lp7_wdone
.Lp7_w8:
	s_waitcnt vmcnt(8)
.Lp7_wdone:
	s_waitcnt lgkmcnt(0)
	s_barrier
	s_setprio 1
	s_waitcnt lgkmcnt(0)
	v_mfma_f32_16x16x32_bf16 v[92:95], v[88:91], v[160:163], v[92:95]
	v_mfma_f32_16x16x32_bf16 v[20:23], v[120:123], v[160:163], v[20:23]
	v_mfma_f32_16x16x32_bf16 v[84:87], v[88:91], v[168:171], v[84:87]
	v_mfma_f32_16x16x32_bf16 v[12:15], v[120:123], v[168:171], v[12:15]
	v_mfma_f32_16x16x32_bf16 v[76:79], v[88:91], v[192:195], v[76:79]
	v_mfma_f32_16x16x32_bf16 v[4:7], v[120:123], v[192:195], v[4:7]
	v_mfma_f32_16x16x32_bf16 v[40:43], v[88:91], v[218:221], v[40:43]
	v_mfma_f32_16x16x32_bf16 v[24:27], v[120:123], v[218:221], v[24:27]
	v_mfma_f32_16x16x32_bf16 v[92:95], v[96:99], v[164:167], v[92:95]
	v_mfma_f32_16x16x32_bf16 v[20:23], v[124:127], v[164:167], v[20:23]
	v_mfma_f32_16x16x32_bf16 v[84:87], v[96:99], v[172:175], v[84:87]
	v_mfma_f32_16x16x32_bf16 v[12:15], v[124:127], v[172:175], v[12:15]
	v_mfma_f32_16x16x32_bf16 v[76:79], v[96:99], v[196:199], v[76:79]
	v_mfma_f32_16x16x32_bf16 v[4:7], v[124:127], v[196:199], v[4:7]
	v_mfma_f32_16x16x32_bf16 v[96:99], v[96:99], v[222:225], v[40:43]
	v_mfma_f32_16x16x32_bf16 v[24:27], v[124:127], v[222:225], v[24:27]
	s_setprio 0
	s_setprio 1
	v_mfma_f32_16x16x32_bf16 v[40:43], v[128:131], v[160:163], v[44:47]
	v_mfma_f32_16x16x32_bf16 v[88:91], v[132:135], v[164:167], v[40:43]
	v_mfma_f32_16x16x32_bf16 v[40:43], v[128:131], v[168:171], v[80:83]
	v_mfma_f32_16x16x32_bf16 v[80:83], v[132:135], v[172:175], v[40:43]
	v_mfma_f32_16x16x32_bf16 v[40:43], v[128:131], v[192:195], v[72:75]
	v_mfma_f32_16x16x32_bf16 v[16:19], v[136:139], v[160:163], v[16:19]
	v_mfma_f32_16x16x32_bf16 v[8:11], v[136:139], v[168:171], v[8:11]
	v_mfma_f32_16x16x32_bf16 v[72:75], v[132:135], v[196:199], v[40:43]
	v_mfma_f32_16x16x32_bf16 v[0:3], v[136:139], v[192:195], v[0:3]
	v_mfma_f32_16x16x32_bf16 v[40:43], v[128:131], v[218:221], v[104:107]
	v_mfma_f32_16x16x32_bf16 v[36:39], v[136:139], v[218:221], v[36:39]
	v_mfma_f32_16x16x32_bf16 v[16:19], v[140:143], v[164:167], v[16:19]
	v_mfma_f32_16x16x32_bf16 v[8:11], v[140:143], v[172:175], v[8:11]
	v_mfma_f32_16x16x32_bf16 v[0:3], v[140:143], v[196:199], v[0:3]
	v_mfma_f32_16x16x32_bf16 v[104:107], v[132:135], v[222:225], v[40:43]
	v_mfma_f32_16x16x32_bf16 v[36:39], v[140:143], v[222:225], v[36:39]
	s_setprio 0
	s_barrier
	s_add_i32 s24, s24, 2
	s_add_u32 s0, s0, 0x100
	s_addc_u32 s1, s1, 0
	s_add_u32 s22, s22, 0x100
	s_addc_u32 s23, s23, 0
	s_cmp_gt_u32 s24, 13
	s_cbranch_scc0 .LBB0_685
	s_and_b64 vcc, exec, s[38:39]
	s_cbranch_vccz .LBB0_688
	s_barrier
.LBB0_688:
	s_mul_hi_i32 s0, s20, 0x3e0f83e1
	s_lshr_b32 s1, s0, 31
	s_ashr_i32 s0, s0, 3
	s_add_i32 s0, s0, s1
	s_mul_i32 s1, s0, 33
	s_sub_i32 s16, s20, s1
	s_mul_i32 s1, s16, 0xfe
	s_lshl_b32 s0, s0, 13
	s_min_i32 s41, s1, 0x1f00
	s_add_i32 s41, s41, s0
	v_add_u32_e32 v194, s41, v200
	s_waitcnt vmcnt(6)
	v_mov_b32_e32 v44, v236
	v_mov_b32_e32 v45, v237
	v_mov_b32_e32 v46, v238
	v_mov_b32_e32 v47, v239
	v_mov_b32_e32 v140, v240
	v_mov_b32_e32 v141, v241
	v_mov_b32_e32 v142, v242
	v_mov_b32_e32 v143, v243
	v_mov_b32_e32 v40, v246
	v_mov_b32_e32 v41, v247
	v_mov_b32_e32 v42, v248
	v_mov_b32_e32 v43, v249
	v_mov_b32_e32 v136, v250
	v_mov_b32_e32 v137, v251
	v_mov_b32_e32 v138, v252
	v_mov_b32_e32 v139, v253
	v_mov_b32_e32 v132, v244
	v_mov_b32_e32 v133, v245
	v_mov_b32_e32 v198, v208
	v_mov_b32_e32 v221, v203
	v_mov_b32_e32 v220, v204
	v_mov_b32_e32 v219, v205
	v_mov_b32_e32 v218, v206
	v_mov_b32_e32 v199, v207
	v_fmamk_f32 v120, v132, 0x3a800000, v215
	v_rsq_f32_e32 v120, v120
	v_fmamk_f32 v121, v133, 0x3a800000, v215
	v_rsq_f32_e32 v122, v121
	v_pk_fma_f32 v[162:163], v[118:119], v[120:121], v[142:143] op_sel_hi:[1,0,1]
	v_pk_fma_f32 v[160:161], v[116:117], v[120:121], v[140:141] op_sel_hi:[1,0,1]
	v_pk_fma_f32 v[66:67], v[66:67], v[120:121], v[46:47] op_sel_hi:[1,0,1]
	v_pk_fma_f32 v[64:65], v[64:65], v[120:121], v[44:45] op_sel_hi:[1,0,1]
	v_pk_fma_f32 v[166:167], v[114:115], v[120:121], v[138:139] op_sel_hi:[1,0,1]
	v_pk_fma_f32 v[164:165], v[112:113], v[120:121], v[136:137] op_sel_hi:[1,0,1]
	v_pk_fma_f32 v[70:71], v[70:71], v[120:121], v[42:43] op_sel_hi:[1,0,1]
	v_pk_fma_f32 v[68:69], v[68:69], v[120:121], v[40:41] op_sel_hi:[1,0,1]
	v_pk_fma_f32 v[98:99], v[98:99], v[122:123], v[142:143] op_sel_hi:[1,0,1]
	v_pk_fma_f32 v[96:97], v[96:97], v[122:123], v[140:141] op_sel_hi:[1,0,1]
	v_pk_fma_f32 v[26:27], v[26:27], v[122:123], v[46:47] op_sel_hi:[1,0,1]
	v_pk_fma_f32 v[24:25], v[24:25], v[122:123], v[44:45] op_sel_hi:[1,0,1]
	v_pk_fma_f32 v[106:107], v[106:107], v[122:123], v[138:139] op_sel_hi:[1,0,1]
	v_pk_fma_f32 v[104:105], v[104:105], v[122:123], v[136:137] op_sel_hi:[1,0,1]
	v_pk_fma_f32 v[38:39], v[38:39], v[122:123], v[42:43] op_sel_hi:[1,0,1]
	v_pk_fma_f32 v[36:37], v[36:37], v[122:123], v[40:41] op_sel_hi:[1,0,1]
	s_and_saveexec_b64 s[0:1], s[4:5]
	s_cbranch_execz .LBB0_690
	ds_write_b128 v216, v[160:163]
	ds_write_b128 v216, v[64:67] offset:16
	ds_write_b128 v216, v[164:167] offset:32
	ds_write_b128 v216, v[68:71] offset:48
	ds_write_b128 v217, v[96:99]
	ds_write_b128 v217, v[24:27] offset:16
	ds_write_b128 v217, v[104:107] offset:32
	ds_write_b128 v217, v[36:39] offset:48

.LBB0_694:
	s_or_b64 exec, exec, s[16:17]
	v_fmamk_f32 v152, v221, 0x3a800000, v215
	v_rsq_f32_e32 v152, v152
	v_mov_b32_e32 v158, 0
	v_mov_b32_e32 v155, 0
	v_mov_b32_e32 v159, 0
	v_pk_fma_f32 v[150:151], v[150:151], v[152:153], v[142:143] op_sel_hi:[1,0,1]
	v_pk_fma_f32 v[148:149], v[148:149], v[152:153], v[140:141] op_sel_hi:[1,0,1]
	v_pk_fma_f32 v[146:147], v[146:147], v[152:153], v[138:139] op_sel_hi:[1,0,1]
	v_pk_fma_f32 v[144:145], v[144:145], v[152:153], v[136:137] op_sel_hi:[1,0,1]
	v_mov_b32_e32 v153, 0
	v_mov_b32_e32 v156, 0
	v_mov_b32_e32 v168, 0
	v_mov_b32_e32 v157, 0
	v_mov_b32_e32 v169, 0
	v_mov_b32_e32 v172, 0
	v_mov_b32_e32 v174, 0
	v_mov_b32_e32 v173, 0
	v_mov_b32_e32 v221, 0
	v_mov_b32_e32 v175, 0
	v_mov_b32_e32 v235, 0
	v_mov_b32_e32 v232, 0
	v_mov_b32_e32 v238, 0
	v_mov_b32_dpp v153, v148 row_ror:1 row_mask:0xf bank_mask:0xf
	v_mov_b32_dpp v158, v148 row_ror:2 row_mask:0xf bank_mask:0xf
	v_mov_b32_dpp v155, v149 row_ror:1 row_mask:0xf bank_mask:0xf
	v_mov_b32_dpp v159, v149 row_ror:2 row_mask:0xf bank_mask:0xf
	v_mov_b32_dpp v156, v150 row_ror:1 row_mask:0xf bank_mask:0xf
	v_mov_b32_dpp v168, v150 row_ror:2 row_mask:0xf bank_mask:0xf
	v_mov_b32_dpp v157, v151 row_ror:1 row_mask:0xf bank_mask:0xf
	v_mov_b32_dpp v169, v151 row_ror:2 row_mask:0xf bank_mask:0xf
	v_mov_b32_dpp v172, v144 row_ror:1 row_mask:0xf bank_mask:0xf
	v_mov_b32_dpp v174, v144 row_ror:2 row_mask:0xf bank_mask:0xf
	v_mov_b32_dpp v173, v145 row_ror:1 row_mask:0xf bank_mask:0xf
	v_mov_b32_dpp v221, v145 row_ror:2 row_mask:0xf bank_mask:0xf
	v_mov_b32_dpp v175, v146 row_ror:1 row_mask:0xf bank_mask:0xf
	v_mov_b32_dpp v235, v146 row_ror:2 row_mask:0xf bank_mask:0xf
	v_mov_b32_dpp v232, v147 row_ror:1 row_mask:0xf bank_mask:0xf
	v_mov_b32_dpp v238, v147 row_ror:2 row_mask:0xf bank_mask:0xf
	v_or_b32_e32 v203, 16, v200
	v_cmp_le_u32_e64 s[16:17], s46, v203
	v_add_u32_e32 v154, s41, v203
	s_and_saveexec_b64 s[18:19], s[16:17]
	s_cbranch_execz .LBB0_696
	v_cndmask_b32_e64 v170, v233, v174, s[8:9]
	v_cndmask_b32_e64 v171, v236, v221, s[8:9]
	v_cndmask_b32_e64 v230, v172, v230, s[6:7]
	v_cndmask_b32_e64 v231, v173, v231, s[6:7]
	s_waitcnt vmcnt(4)
	v_pk_mul_f32 v[170:171], v[124:125], v[170:171]
	v_cndmask_b32_e64 v224, v156, v224, s[6:7]
	s_waitcnt vmcnt(2)
	v_pk_fma_f32 v[170:171], v[128:129], v[230:231], v[170:171]
	v_cndmask_b32_e64 v225, v157, v225, s[6:7]
	s_waitcnt vmcnt(0)
	v_pk_fma_f32 v[144:145], v[144:145], v[132:133], v[170:171]
	v_cndmask_b32_e64 v170, v226, v158, s[8:9]
	v_cndmask_b32_e64 v171, v227, v159, s[8:9]
	v_cndmask_b32_e64 v226, v228, v168, s[8:9]
	v_cndmask_b32_e64 v227, v229, v169, s[8:9]
	v_pk_mul_f32 v[226:227], v[122:123], v[226:227]
	v_pk_mul_f32 v[170:171], v[120:121], v[170:171]
	v_pk_fma_f32 v[224:225], v[114:115], v[224:225], v[226:227]
	v_cndmask_b32_e64 v222, v153, v222, s[6:7]
	v_pk_fma_f32 v[150:151], v[150:151], v[118:119], v[224:225]
	v_cndmask_b32_e64 v223, v155, v223, s[6:7]
	v_mul_f32_e32 v208, 0xbfb8aa3b, v151
	v_exp_f32_e32 v208, v208
	v_pk_fma_f32 v[170:171], v[112:113], v[222:223], v[170:171]
	v_mul_f32_e32 v222, 0xbfb8aa3b, v150
	v_cndmask_b32_e64 v242, v239, v235, s[8:9]
	v_add_f32_e32 v208, 1.0, v208
	v_rcp_f32_e32 v208, v208
	v_cndmask_b32_e64 v243, v240, v238, s[8:9]
	v_exp_f32_e32 v222, v222
	v_cndmask_b32_e64 v236, v175, v234, s[6:7]
	v_cndmask_b32_e64 v237, v232, v237, s[6:7]
	v_pk_mul_f32 v[240:241], v[126:127], v[242:243]
	v_pk_fma_f32 v[148:149], v[148:149], v[116:117], v[170:171]
	v_pk_fma_f32 v[236:237], v[130:131], v[236:237], v[240:241]
	v_mul_f32_e32 v151, v151, v208
	v_pk_fma_f32 v[146:147], v[146:147], v[134:135], v[236:237]
	v_mul_f32_e32 v170, 0xbfb8aa3b, v149
	v_mul_f32_e32 v147, v151, v147
	v_add_f32_e32 v151, 1.0, v222
	v_mul_f32_e32 v171, 0xbfb8aa3b, v148
	v_rcp_f32_e32 v151, v151
	v_exp_f32_e32 v170, v170
	v_exp_f32_e32 v171, v171
	v_mul_f32_e32 v150, v150, v151
	v_add_f32_e32 v151, 1.0, v170
	v_add_f32_e32 v170, 1.0, v171
	v_rcp_f32_e32 v151, v151
	v_rcp_f32_e32 v170, v170
	v_mul_f32_e32 v146, v150, v146
	v_mul_f32_e32 v149, v149, v151
	v_mul_f32_e32 v148, v148, v170
	v_mul_f32_e32 v145, v149, v145
	v_mul_f32_e32 v144, v148, v144
	v_cvt_pk_bf16_f32 v144, v144, v145
	v_cvt_pk_bf16_f32 v145, v146, v147
	v_mov_b64_e32 v[146:147], s[30:31]
	v_mad_i64_i32 v[146:147], s[20:21], v154, s67, v[146:147]
	v_lshl_add_u64 v[146:147], v[192:193], 1, v[146:147]
	global_store_dwordx2 v[146:147], v[144:145], off
.LBB0_696:
	s_or_b64 exec, exec, s[18:19]
	v_fmamk_f32 v144, v220, 0x3a800000, v215
	v_rsq_f32_e32 v144, v144
	v_mov_b32_e32 v150, 0
	v_mov_b32_e32 v146, 0
	v_mov_b32_e32 v151, 0
	v_pk_fma_f32 v[110:111], v[110:111], v[144:145], v[142:143] op_sel_hi:[1,0,1]
	v_pk_fma_f32 v[108:109], v[108:109], v[144:145], v[140:141] op_sel_hi:[1,0,1]
	v_pk_fma_f32 v[102:103], v[102:103], v[144:145], v[138:139] op_sel_hi:[1,0,1]
	v_pk_fma_f32 v[100:101], v[100:101], v[144:145], v[136:137] op_sel_hi:[1,0,1]
	v_mov_b32_e32 v145, 0
	v_mov_b32_e32 v148, 0
	v_mov_b32_e32 v170, 0
	v_mov_b32_e32 v149, 0
	v_mov_b32_e32 v171, 0
	v_mov_b32_e32 v220, 0
	v_mov_b32_e32 v223, 0
	v_mov_b32_e32 v222, 0
	v_mov_b32_e32 v225, 0
	v_mov_b32_e32 v224, 0
	v_mov_b32_e32 v227, 0
	v_mov_b32_e32 v226, 0
	v_mov_b32_e32 v228, 0
	v_mov_b32_dpp v145, v108 row_ror:1 row_mask:0xf bank_mask:0xf
	v_mov_b32_dpp v150, v108 row_ror:2 row_mask:0xf bank_mask:0xf
	v_mov_b32_dpp v146, v109 row_ror:1 row_mask:0xf bank_mask:0xf
	v_mov_b32_dpp v151, v109 row_ror:2 row_mask:0xf bank_mask:0xf
	v_mov_b32_dpp v148, v110 row_ror:1 row_mask:0xf bank_mask:0xf
	v_mov_b32_dpp v170, v110 row_ror:2 row_mask:0xf bank_mask:0xf
	v_mov_b32_dpp v149, v111 row_ror:1 row_mask:0xf bank_mask:0xf
	v_mov_b32_dpp v171, v111 row_ror:2 row_mask:0xf bank_mask:0xf
	v_mov_b32_dpp v220, v100 row_ror:1 row_mask:0xf bank_mask:0xf
	v_mov_b32_dpp v223, v100 row_ror:2 row_mask:0xf bank_mask:0xf
	v_mov_b32_dpp v222, v101 row_ror:1 row_mask:0xf bank_mask:0xf
	v_mov_b32_dpp v225, v101 row_ror:2 row_mask:0xf bank_mask:0xf
	v_mov_b32_dpp v224, v102 row_ror:1 row_mask:0xf bank_mask:0xf
	v_mov_b32_dpp v227, v102 row_ror:2 row_mask:0xf bank_mask:0xf
	v_mov_b32_dpp v226, v103 row_ror:1 row_mask:0xf bank_mask:0xf
	v_mov_b32_dpp v228, v103 row_ror:2 row_mask:0xf bank_mask:0xf
	v_or_b32_e32 v204, 32, v200
	v_cmp_le_u32_e64 s[18:19], s46, v204
	v_add_u32_e32 v147, s41, v204
	s_and_saveexec_b64 s[20:21], s[18:19]
	s_cbranch_execz .LBB0_698
	v_cndmask_b32_e64 v168, v168, v170, s[8:9]
	v_cndmask_b32_e64 v169, v169, v171, s[8:9]
	s_waitcnt vmcnt(5)
	v_pk_mul_f32 v[168:169], v[122:123], v[168:169]
	v_cndmask_b32_e64 v156, v148, v156, s[6:7]
	v_cndmask_b32_e64 v157, v149, v157, s[6:7]
	s_waitcnt vmcnt(3)
	v_pk_fma_f32 v[156:157], v[114:115], v[156:157], v[168:169]
	v_cndmask_b32_e64 v234, v235, v227, s[8:9]
	s_waitcnt vmcnt(1)
	v_pk_fma_f32 v[110:111], v[110:111], v[118:119], v[156:157]
	v_cndmask_b32_e64 v157, v146, v155, s[6:7]
	v_mul_f32_e32 v156, 0xbfb8aa3b, v111
	v_exp_f32_e32 v168, v156
	v_cndmask_b32_e64 v156, v145, v153, s[6:7]
	v_mul_f32_e32 v155, 0xbfb8aa3b, v110
	v_cndmask_b32_e64 v235, v238, v228, s[8:9]
	v_add_f32_e32 v153, 1.0, v168
	v_rcp_f32_e32 v153, v153
	v_cndmask_b32_e64 v158, v158, v150, s[8:9]
	v_cndmask_b32_e64 v159, v159, v151, s[8:9]
	v_exp_f32_e32 v155, v155
	v_cndmask_b32_e64 v230, v174, v223, s[8:9]
	v_cndmask_b32_e64 v174, v224, v175, s[6:7]
	v_cndmask_b32_e64 v175, v226, v232, s[6:7]
	v_pk_mul_f32 v[232:233], v[126:127], v[234:235]
	v_pk_mul_f32 v[158:159], v[120:121], v[158:159]
	v_pk_fma_f32 v[174:175], v[130:131], v[174:175], v[232:233]
	v_pk_fma_f32 v[156:157], v[112:113], v[156:157], v[158:159]
	s_waitcnt vmcnt(0)
	v_pk_fma_f32 v[102:103], v[102:103], v[134:135], v[174:175]
	v_pk_fma_f32 v[108:109], v[108:109], v[116:117], v[156:157]
	v_mul_f32_e32 v111, v111, v153
	v_mul_f32_e32 v103, v111, v103
	v_add_f32_e32 v111, 1.0, v155
	v_mul_f32_e32 v153, 0xbfb8aa3b, v109
	v_mul_f32_e32 v155, 0xbfb8aa3b, v108
	v_rcp_f32_e32 v111, v111
	v_exp_f32_e32 v153, v153
	v_exp_f32_e32 v155, v155
	v_cndmask_b32_e64 v231, v221, v225, s[8:9]
	v_mul_f32_e32 v110, v110, v111
	v_add_f32_e32 v111, 1.0, v153
	v_add_f32_e32 v153, 1.0, v155
	v_rcp_f32_e32 v111, v111
	v_rcp_f32_e32 v153, v153
	v_cndmask_b32_e64 v172, v220, v172, s[6:7]
	v_cndmask_b32_e64 v173, v222, v173, s[6:7]
	v_pk_mul_f32 v[230:231], v[124:125], v[230:231]
	v_mul_f32_e32 v109, v109, v111
	v_pk_fma_f32 v[172:173], v[128:129], v[172:173], v[230:231]
	v_mul_f32_e32 v108, v108, v153
	v_pk_fma_f32 v[100:101], v[100:101], v[132:133], v[172:173]
	v_mul_f32_e32 v102, v110, v102
	v_mul_f32_e32 v101, v109, v101
	v_mul_f32_e32 v100, v108, v100
	v_cvt_pk_bf16_f32 v100, v100, v101
	v_cvt_pk_bf16_f32 v101, v102, v103
	v_mov_b64_e32 v[102:103], s[30:31]
	v_mad_i64_i32 v[102:103], s[22:23], v147, s67, v[102:103]
	v_lshl_add_u64 v[102:103], v[192:193], 1, v[102:103]
	global_store_dwordx2 v[102:103], v[100:101], off
.LBB0_698:
	s_or_b64 exec, exec, s[20:21]
	v_mov_b32_e32 v100, 0
	v_mov_b32_e32 v108, 0
	v_mov_b32_e32 v101, 0
	v_mov_b32_e32 v110, 0
	v_mov_b32_e32 v102, 0
	v_mov_b32_e32 v111, 0
	v_mov_b32_e32 v103, 0
	v_mov_b32_e32 v153, 0
	v_mov_b32_e32 v155, 0
	v_mov_b32_e32 v157, 0
	v_mov_b32_e32 v156, 0
	v_mov_b32_e32 v159, 0
	v_mov_b32_e32 v158, 0
	v_mov_b32_e32 v169, 0
	v_mov_b32_e32 v168, 0
	v_mov_b32_e32 v172, 0
	v_mov_b32_dpp v100, v160 row_ror:1 row_mask:0xf bank_mask:0xf
	v_mov_b32_dpp v108, v160 row_ror:2 row_mask:0xf bank_mask:0xf
	v_mov_b32_dpp v101, v161 row_ror:1 row_mask:0xf bank_mask:0xf
	v_mov_b32_dpp v110, v161 row_ror:2 row_mask:0xf bank_mask:0xf
	v_mov_b32_dpp v102, v162 row_ror:1 row_mask:0xf bank_mask:0xf
	v_mov_b32_dpp v111, v162 row_ror:2 row_mask:0xf bank_mask:0xf
	v_mov_b32_dpp v103, v163 row_ror:1 row_mask:0xf bank_mask:0xf
	v_mov_b32_dpp v153, v163 row_ror:2 row_mask:0xf bank_mask:0xf
	v_mov_b32_dpp v155, v164 row_ror:1 row_mask:0xf bank_mask:0xf
	v_mov_b32_dpp v157, v164 row_ror:2 row_mask:0xf bank_mask:0xf
	v_mov_b32_dpp v156, v165 row_ror:1 row_mask:0xf bank_mask:0xf
	v_mov_b32_dpp v159, v165 row_ror:2 row_mask:0xf bank_mask:0xf
	v_mov_b32_dpp v158, v166 row_ror:1 row_mask:0xf bank_mask:0xf
	v_mov_b32_dpp v169, v166 row_ror:2 row_mask:0xf bank_mask:0xf
	v_mov_b32_dpp v168, v167 row_ror:1 row_mask:0xf bank_mask:0xf
	v_mov_b32_dpp v172, v167 row_ror:2 row_mask:0xf bank_mask:0xf
	v_or_b32_e32 v205, 48, v200
	v_cmp_le_u32_e64 s[20:21], s46, v205
	v_add_u32_e32 v109, s41, v205
	s_and_saveexec_b64 s[22:23], s[20:21]
	s_cbranch_execz .LBB0_700
	v_cndmask_b32_e64 v151, v151, v110, s[8:9]
	v_cndmask_b32_e64 v110, v170, v111, s[8:9]
	v_cndmask_b32_e64 v111, v171, v153, s[8:9]
	s_waitcnt vmcnt(5)
	v_pk_mul_f32 v[110:111], v[122:123], v[110:111]
	v_cndmask_b32_e64 v102, v102, v148, s[6:7]
	v_cndmask_b32_e64 v103, v103, v149, s[6:7]
	s_waitcnt vmcnt(3)
	v_pk_fma_f32 v[102:103], v[114:115], v[102:103], v[110:111]
	v_cndmask_b32_e64 v150, v150, v108, s[8:9]
	s_waitcnt vmcnt(1)
	v_pk_fma_f32 v[102:103], v[162:163], v[118:119], v[102:103]
	v_pk_mul_f32 v[150:151], v[120:121], v[150:151]
	v_mul_f32_e32 v108, 0xbfb8aa3b, v103
	v_exp_f32_e32 v108, v108
	v_mul_f32_e32 v110, 0xbfb8aa3b, v102
	v_exp_f32_e32 v110, v110
	v_cndmask_b32_e64 v100, v100, v145, s[6:7]
	v_add_f32_e32 v108, 1.0, v108
	v_rcp_f32_e32 v108, v108
	v_cndmask_b32_e64 v101, v101, v146, s[6:7]
	v_pk_fma_f32 v[100:101], v[112:113], v[100:101], v[150:151]
	v_cndmask_b32_e64 v174, v223, v157, s[8:9]
	v_pk_fma_f32 v[100:101], v[160:161], v[116:117], v[100:101]
	v_mul_f32_e32 v103, v103, v108
	v_add_f32_e32 v108, 1.0, v110
	v_mul_f32_e32 v110, 0xbfb8aa3b, v101
	v_mul_f32_e32 v111, 0xbfb8aa3b, v100
	v_rcp_f32_e32 v108, v108
	v_exp_f32_e32 v110, v110
	v_exp_f32_e32 v111, v111
	v_cndmask_b32_e64 v175, v225, v159, s[8:9]
	v_mul_f32_e32 v102, v102, v108
	v_add_f32_e32 v108, 1.0, v110
	v_add_f32_e32 v110, 1.0, v111
	v_rcp_f32_e32 v108, v108
	v_rcp_f32_e32 v110, v110
	v_cndmask_b32_e64 v230, v227, v169, s[8:9]
	v_cndmask_b32_e64 v231, v228, v172, s[8:9]
	v_cndmask_b32_e64 v172, v155, v220, s[6:7]
	v_cndmask_b32_e64 v173, v156, v222, s[6:7]
	v_cndmask_b32_e64 v156, v158, v224, s[6:7]
	v_cndmask_b32_e64 v157, v168, v226, s[6:7]
	v_pk_mul_f32 v[158:159], v[124:125], v[174:175]
	v_pk_mul_f32 v[168:169], v[126:127], v[230:231]
	v_pk_fma_f32 v[158:159], v[128:129], v[172:173], v[158:159]
	v_pk_fma_f32 v[156:157], v[130:131], v[156:157], v[168:169]
	s_waitcnt vmcnt(0)
	v_pk_fma_f32 v[158:159], v[164:165], v[132:133], v[158:159]
	v_pk_fma_f32 v[156:157], v[166:167], v[134:135], v[156:157]
	v_mul_f32_e32 v101, v101, v108
	v_mul_f32_e32 v100, v100, v110
	v_mul_f32_e32 v103, v103, v157
	v_mul_f32_e32 v102, v102, v156
	v_mul_f32_e32 v101, v101, v159
	v_mul_f32_e32 v100, v100, v158
	v_cvt_pk_bf16_f32 v100, v100, v101
	v_cvt_pk_bf16_f32 v101, v102, v103
	v_mov_b64_e32 v[102:103], s[30:31]
	v_mad_i64_i32 v[102:103], s[24:25], v109, s67, v[102:103]
	v_lshl_add_u64 v[102:103], v[192:193], 1, v[102:103]
	global_store_dwordx2 v[102:103], v[100:101], off
.LBB0_700:
	s_or_b64 exec, exec, s[22:23]
	v_fmamk_f32 v100, v219, 0x3a800000, v215
	v_rsq_f32_e32 v108, v100
	v_mov_b32_e32 v100, 0
	v_mov_b32_e32 v110, 0
	v_mov_b32_e32 v101, 0
	v_pk_fma_f32 v[94:95], v[94:95], v[108:109], v[142:143] op_sel_hi:[1,0,1]
	v_pk_fma_f32 v[92:93], v[92:93], v[108:109], v[140:141] op_sel_hi:[1,0,1]
	v_pk_fma_f32 v[90:91], v[90:91], v[108:109], v[138:139] op_sel_hi:[1,0,1]
	v_pk_fma_f32 v[88:89], v[88:89], v[108:109], v[136:137] op_sel_hi:[1,0,1]
	v_mov_b32_e32 v145, 0
	v_mov_b32_e32 v102, 0
	v_mov_b32_e32 v150, 0
	v_mov_b32_e32 v103, 0
	v_mov_b32_e32 v151, 0
	v_mov_b32_e32 v153, 0
	v_mov_b32_e32 v156, 0
	v_mov_b32_e32 v155, 0
	v_mov_b32_e32 v158, 0
	v_mov_b32_e32 v157, 0
	v_mov_b32_e32 v160, 0
	v_mov_b32_e32 v159, 0
	v_mov_b32_e32 v161, 0
	v_mov_b32_dpp v100, v92 row_ror:1 row_mask:0xf bank_mask:0xf
	v_mov_b32_dpp v110, v92 row_ror:2 row_mask:0xf bank_mask:0xf
	v_mov_b32_dpp v101, v93 row_ror:1 row_mask:0xf bank_mask:0xf
	v_mov_b32_dpp v145, v93 row_ror:2 row_mask:0xf bank_mask:0xf
	v_mov_b32_dpp v102, v94 row_ror:1 row_mask:0xf bank_mask:0xf
	v_mov_b32_dpp v150, v94 row_ror:2 row_mask:0xf bank_mask:0xf
	v_mov_b32_dpp v103, v95 row_ror:1 row_mask:0xf bank_mask:0xf
	v_mov_b32_dpp v151, v95 row_ror:2 row_mask:0xf bank_mask:0xf
	v_mov_b32_dpp v153, v88 row_ror:1 row_mask:0xf bank_mask:0xf
	v_mov_b32_dpp v156, v88 row_ror:2 row_mask:0xf bank_mask:0xf
	v_mov_b32_dpp v155, v89 row_ror:1 row_mask:0xf bank_mask:0xf
	v_mov_b32_dpp v158, v89 row_ror:2 row_mask:0xf bank_mask:0xf
	v_mov_b32_dpp v157, v90 row_ror:1 row_mask:0xf bank_mask:0xf
	v_mov_b32_dpp v160, v90 row_ror:2 row_mask:0xf bank_mask:0xf
	v_mov_b32_dpp v159, v91 row_ror:1 row_mask:0xf bank_mask:0xf
	v_mov_b32_dpp v161, v91 row_ror:2 row_mask:0xf bank_mask:0xf
	v_add_u32_e32 v206, 0x80, v200
	v_cmp_le_u32_e64 s[22:23], s46, v206
	v_add_u32_e32 v149, s64, v202
	v_add_u32_e32 v111, s41, v206
	s_and_saveexec_b64 s[24:25], s[22:23]
	s_cbranch_execz .LBB0_702
	ds_read_b128 v[162:165], v149 offset:288
	ds_read_b128 v[166:169], v149 offset:32
	ds_read_b128 v[170:173], v149
	ds_read_b128 v[220:223], v149 offset:256
	s_waitcnt lgkmcnt(2)
	v_cndmask_b32_e64 v146, v165, v169, s[6:7]
	v_cndmask_b32_e64 v148, v164, v168, s[6:7]
	v_cndmask_b32_e64 v168, v148, v160, s[8:9]
	v_cndmask_b32_e64 v169, v146, v161, s[8:9]
	v_cndmask_b32_e64 v167, v163, v167, s[6:7]
	v_cndmask_b32_e64 v166, v162, v166, s[6:7]
	v_cndmask_b32_e64 v164, v157, v164, s[6:7]
	v_cndmask_b32_e64 v165, v159, v165, s[6:7]
	s_waitcnt vmcnt(4)
	v_pk_mul_f32 v[168:169], v[126:127], v[168:169]
	v_cndmask_b32_e64 v166, v166, v156, s[8:9]
	v_cndmask_b32_e64 v167, v167, v158, s[8:9]
	s_waitcnt vmcnt(2)
	v_pk_fma_f32 v[164:165], v[130:131], v[164:165], v[168:169]
	s_waitcnt lgkmcnt(0)
	v_cndmask_b32_e64 v146, v223, v173, s[6:7]
	v_cndmask_b32_e64 v148, v222, v172, s[6:7]
	v_cndmask_b32_e64 v162, v153, v162, s[6:7]
	v_cndmask_b32_e64 v163, v155, v163, s[6:7]
	v_pk_mul_f32 v[166:167], v[124:125], v[166:167]
	s_waitcnt vmcnt(0)
	v_pk_fma_f32 v[90:91], v[90:91], v[134:135], v[164:165]
	v_cndmask_b32_e64 v164, v148, v150, s[8:9]
	v_cndmask_b32_e64 v165, v146, v151, s[8:9]
	v_pk_fma_f32 v[162:163], v[128:129], v[162:163], v[166:167]
	v_pk_mul_f32 v[164:165], v[122:123], v[164:165]
	v_cndmask_b32_e64 v166, v102, v222, s[6:7]
	v_cndmask_b32_e64 v167, v103, v223, s[6:7]
	v_pk_fma_f32 v[164:165], v[114:115], v[166:167], v[164:165]
	v_pk_fma_f32 v[88:89], v[88:89], v[132:133], v[162:163]
	v_pk_fma_f32 v[94:95], v[94:95], v[118:119], v[164:165]
	v_cndmask_b32_e64 v163, v221, v171, s[6:7]
	v_mul_f32_e32 v146, 0xbfb8aa3b, v95
	v_exp_f32_e32 v146, v146
	v_cndmask_b32_e64 v162, v220, v170, s[6:7]
	v_mul_f32_e32 v148, 0xbfb8aa3b, v94
	v_cndmask_b32_e64 v162, v162, v110, s[8:9]
	v_add_f32_e32 v146, 1.0, v146
	v_rcp_f32_e32 v146, v146
	v_cndmask_b32_e64 v163, v163, v145, s[8:9]
	v_exp_f32_e32 v148, v148
	v_pk_mul_f32 v[162:163], v[120:121], v[162:163]
	v_cndmask_b32_e64 v164, v100, v220, s[6:7]
	v_cndmask_b32_e64 v165, v101, v221, s[6:7]
	v_pk_fma_f32 v[162:163], v[112:113], v[164:165], v[162:163]
	v_mul_f32_e32 v95, v95, v146
	v_pk_fma_f32 v[92:93], v[92:93], v[116:117], v[162:163]
	v_mul_f32_e32 v91, v91, v95
	v_add_f32_e32 v95, 1.0, v148
	v_mul_f32_e32 v146, 0xbfb8aa3b, v93
	v_mul_f32_e32 v148, 0xbfb8aa3b, v92
	v_rcp_f32_e32 v95, v95
	v_exp_f32_e32 v146, v146
	v_exp_f32_e32 v148, v148
	v_mul_f32_e32 v94, v94, v95
	v_add_f32_e32 v95, 1.0, v146
	v_add_f32_e32 v146, 1.0, v148
	v_rcp_f32_e32 v95, v95
	v_rcp_f32_e32 v146, v146
	v_mul_f32_e32 v90, v90, v94
	v_mul_f32_e32 v93, v93, v95
	v_mul_f32_e32 v92, v92, v146
	v_mul_f32_e32 v89, v89, v93
	v_mul_f32_e32 v88, v88, v92
	v_cvt_pk_bf16_f32 v88, v88, v89
	v_cvt_pk_bf16_f32 v89, v90, v91
	v_mov_b64_e32 v[90:91], s[30:31]
	v_mad_i64_i32 v[90:91], s[26:27], v111, s67, v[90:91]
	v_lshl_add_u64 v[90:91], v[192:193], 1, v[90:91]
	global_store_dwordx2 v[90:91], v[88:89], off
.LBB0_702:
	s_or_b64 exec, exec, s[24:25]
	v_fmamk_f32 v88, v218, 0x3a800000, v215
	v_rsq_f32_e32 v146, v88
	v_mov_b32_e32 v88, 0
	v_mov_b32_e32 v92, 0
	v_mov_b32_e32 v89, 0
	v_pk_fma_f32 v[86:87], v[86:87], v[146:147], v[142:143] op_sel_hi:[1,0,1]
	v_pk_fma_f32 v[84:85], v[84:85], v[146:147], v[140:141] op_sel_hi:[1,0,1]
	v_pk_fma_f32 v[82:83], v[82:83], v[146:147], v[138:139] op_sel_hi:[1,0,1]
	v_pk_fma_f32 v[80:81], v[80:81], v[146:147], v[136:137] op_sel_hi:[1,0,1]
	v_mov_b32_e32 v93, 0
	v_mov_b32_e32 v90, 0
	v_mov_b32_e32 v94, 0
	v_mov_b32_e32 v91, 0
	v_mov_b32_e32 v95, 0
	v_mov_b32_e32 v162, 0
	v_mov_b32_e32 v164, 0
	v_mov_b32_e32 v163, 0
	v_mov_b32_e32 v166, 0
	v_mov_b32_e32 v165, 0
	v_mov_b32_e32 v168, 0
	v_mov_b32_e32 v167, 0
	v_mov_b32_e32 v169, 0
	v_mov_b32_dpp v88, v84 row_ror:1 row_mask:0xf bank_mask:0xf
	v_mov_b32_dpp v92, v84 row_ror:2 row_mask:0xf bank_mask:0xf
	v_mov_b32_dpp v89, v85 row_ror:1 row_mask:0xf bank_mask:0xf
	v_mov_b32_dpp v93, v85 row_ror:2 row_mask:0xf bank_mask:0xf
	v_mov_b32_dpp v90, v86 row_ror:1 row_mask:0xf bank_mask:0xf
	v_mov_b32_dpp v94, v86 row_ror:2 row_mask:0xf bank_mask:0xf
	v_mov_b32_dpp v91, v87 row_ror:1 row_mask:0xf bank_mask:0xf
	v_mov_b32_dpp v95, v87 row_ror:2 row_mask:0xf bank_mask:0xf
	v_mov_b32_dpp v162, v80 row_ror:1 row_mask:0xf bank_mask:0xf
	v_mov_b32_dpp v164, v80 row_ror:2 row_mask:0xf bank_mask:0xf
	v_mov_b32_dpp v163, v81 row_ror:1 row_mask:0xf bank_mask:0xf
	v_mov_b32_dpp v166, v81 row_ror:2 row_mask:0xf bank_mask:0xf
	v_mov_b32_dpp v165, v82 row_ror:1 row_mask:0xf bank_mask:0xf
	v_mov_b32_dpp v168, v82 row_ror:2 row_mask:0xf bank_mask:0xf
	v_mov_b32_dpp v167, v83 row_ror:1 row_mask:0xf bank_mask:0xf
	v_mov_b32_dpp v169, v83 row_ror:2 row_mask:0xf bank_mask:0xf
	v_add_u32_e32 v207, 0x90, v200
	v_cmp_le_u32_e64 s[24:25], s46, v207
	v_add_u32_e32 v148, s41, v207
	s_and_saveexec_b64 s[26:27], s[24:25]
	s_cbranch_execz .LBB0_704
	v_cndmask_b32_e64 v150, v150, v94, s[8:9]
	v_cndmask_b32_e64 v151, v151, v95, s[8:9]
	s_waitcnt vmcnt(5)
	v_pk_mul_f32 v[150:151], v[122:123], v[150:151]
	v_cndmask_b32_e64 v102, v90, v102, s[6:7]
	v_cndmask_b32_e64 v103, v91, v103, s[6:7]
	s_waitcnt vmcnt(3)
	v_pk_fma_f32 v[102:103], v[114:115], v[102:103], v[150:151]
	v_cndmask_b32_e64 v160, v160, v168, s[8:9]
	s_waitcnt vmcnt(1)
	v_pk_fma_f32 v[86:87], v[86:87], v[118:119], v[102:103]
	v_cndmask_b32_e64 v161, v161, v169, s[8:9]
	v_mul_f32_e32 v102, 0xbfb8aa3b, v87
	v_exp_f32_e32 v102, v102
	v_cndmask_b32_e64 v170, v156, v164, s[8:9]
	v_cndmask_b32_e64 v156, v165, v157, s[6:7]
	v_cndmask_b32_e64 v157, v167, v159, s[6:7]
	v_pk_mul_f32 v[160:161], v[126:127], v[160:161]
	v_add_f32_e32 v102, 1.0, v102
	v_pk_fma_f32 v[156:157], v[130:131], v[156:157], v[160:161]
	v_rcp_f32_e32 v102, v102
	v_mul_f32_e32 v103, 0xbfb8aa3b, v86
	s_waitcnt vmcnt(0)
	v_pk_fma_f32 v[82:83], v[82:83], v[134:135], v[156:157]
	v_cndmask_b32_e64 v156, v110, v92, s[8:9]
	v_cndmask_b32_e64 v157, v145, v93, s[8:9]
	v_exp_f32_e32 v103, v103
	v_pk_mul_f32 v[156:157], v[120:121], v[156:157]
	v_cndmask_b32_e64 v100, v88, v100, s[6:7]
	v_cndmask_b32_e64 v101, v89, v101, s[6:7]
	v_pk_fma_f32 v[100:101], v[112:113], v[100:101], v[156:157]
	v_mul_f32_e32 v87, v87, v102
	v_pk_fma_f32 v[84:85], v[84:85], v[116:117], v[100:101]
	v_mul_f32_e32 v83, v87, v83
	v_add_f32_e32 v87, 1.0, v103
	v_mul_f32_e32 v100, 0xbfb8aa3b, v85
	v_mul_f32_e32 v101, 0xbfb8aa3b, v84
	v_rcp_f32_e32 v87, v87
	v_exp_f32_e32 v100, v100
	v_exp_f32_e32 v101, v101
	v_cndmask_b32_e64 v171, v158, v166, s[8:9]
	v_mul_f32_e32 v86, v86, v87
	v_add_f32_e32 v87, 1.0, v100
	v_add_f32_e32 v100, 1.0, v101
	v_rcp_f32_e32 v87, v87
	v_rcp_f32_e32 v100, v100
	v_cndmask_b32_e64 v172, v162, v153, s[6:7]
	v_cndmask_b32_e64 v173, v163, v155, s[6:7]
	v_pk_mul_f32 v[158:159], v[124:125], v[170:171]
	v_mul_f32_e32 v85, v85, v87
	v_pk_fma_f32 v[158:159], v[128:129], v[172:173], v[158:159]
	v_mul_f32_e32 v84, v84, v100
	v_pk_fma_f32 v[80:81], v[80:81], v[132:133], v[158:159]
	v_mul_f32_e32 v82, v86, v82
	v_mul_f32_e32 v81, v85, v81
	v_mul_f32_e32 v80, v84, v80
	v_cvt_pk_bf16_f32 v80, v80, v81
	v_cvt_pk_bf16_f32 v81, v82, v83
	v_mov_b64_e32 v[82:83], s[30:31]
	v_mad_i64_i32 v[82:83], s[28:29], v148, s67, v[82:83]
	v_lshl_add_u64 v[82:83], v[192:193], 1, v[82:83]
	global_store_dwordx2 v[82:83], v[80:81], off
.LBB0_704:
	s_or_b64 exec, exec, s[26:27]
	v_fmamk_f32 v80, v199, 0x3a800000, v215
	v_rsq_f32_e32 v110, v80
	v_mov_b32_e32 v80, 0
	v_mov_b32_e32 v84, 0
	v_mov_b32_e32 v81, 0
	v_pk_fma_f32 v[78:79], v[78:79], v[110:111], v[142:143] op_sel_hi:[1,0,1]
	v_pk_fma_f32 v[76:77], v[76:77], v[110:111], v[140:141] op_sel_hi:[1,0,1]
	v_pk_fma_f32 v[74:75], v[74:75], v[110:111], v[138:139] op_sel_hi:[1,0,1]
	v_pk_fma_f32 v[72:73], v[72:73], v[110:111], v[136:137] op_sel_hi:[1,0,1]
	v_mov_b32_e32 v85, 0
	v_mov_b32_e32 v82, 0
	v_mov_b32_e32 v86, 0
	v_mov_b32_e32 v83, 0
	v_mov_b32_e32 v87, 0
	v_mov_b32_e32 v100, 0
	v_mov_b32_e32 v102, 0
	v_mov_b32_e32 v101, 0
	v_mov_b32_e32 v138, 0
	v_mov_b32_e32 v103, 0
	v_mov_b32_e32 v140, 0
	v_mov_b32_e32 v139, 0
	v_mov_b32_e32 v141, 0
	v_mov_b32_dpp v80, v76 row_ror:1 row_mask:0xf bank_mask:0xf
	v_mov_b32_dpp v84, v76 row_ror:2 row_mask:0xf bank_mask:0xf
	v_mov_b32_dpp v81, v77 row_ror:1 row_mask:0xf bank_mask:0xf
	v_mov_b32_dpp v85, v77 row_ror:2 row_mask:0xf bank_mask:0xf
	v_mov_b32_dpp v82, v78 row_ror:1 row_mask:0xf bank_mask:0xf
	v_mov_b32_dpp v86, v78 row_ror:2 row_mask:0xf bank_mask:0xf
	v_mov_b32_dpp v83, v79 row_ror:1 row_mask:0xf bank_mask:0xf
	v_mov_b32_dpp v87, v79 row_ror:2 row_mask:0xf bank_mask:0xf
	v_mov_b32_dpp v100, v72 row_ror:1 row_mask:0xf bank_mask:0xf
	v_mov_b32_dpp v102, v72 row_ror:2 row_mask:0xf bank_mask:0xf
	v_mov_b32_dpp v101, v73 row_ror:1 row_mask:0xf bank_mask:0xf
	v_mov_b32_dpp v138, v73 row_ror:2 row_mask:0xf bank_mask:0xf
	v_mov_b32_dpp v103, v74 row_ror:1 row_mask:0xf bank_mask:0xf
	v_mov_b32_dpp v140, v74 row_ror:2 row_mask:0xf bank_mask:0xf
	v_mov_b32_dpp v139, v75 row_ror:1 row_mask:0xf bank_mask:0xf
	v_mov_b32_dpp v141, v75 row_ror:2 row_mask:0xf bank_mask:0xf
	v_add_u32_e32 v209, 0xa0, v200
	v_cmp_le_u32_e64 s[26:27], s46, v209
	v_add_u32_e32 v136, s41, v209
	s_and_saveexec_b64 s[28:29], s[26:27]
	s_cbranch_execz .LBB0_706
	v_cndmask_b32_e64 v94, v94, v86, s[8:9]
	v_cndmask_b32_e64 v95, v95, v87, s[8:9]
	s_waitcnt vmcnt(5)
	v_pk_mul_f32 v[94:95], v[122:123], v[94:95]
	v_cndmask_b32_e64 v90, v82, v90, s[6:7]
	v_cndmask_b32_e64 v91, v83, v91, s[6:7]
	s_waitcnt vmcnt(3)
	v_pk_fma_f32 v[90:91], v[114:115], v[90:91], v[94:95]
	v_cndmask_b32_e64 v150, v168, v140, s[8:9]
	s_waitcnt vmcnt(1)
	v_pk_fma_f32 v[78:79], v[78:79], v[118:119], v[90:91]
	v_cndmask_b32_e64 v151, v169, v141, s[8:9]
	v_mul_f32_e32 v90, 0xbfb8aa3b, v79
	v_exp_f32_e32 v90, v90
	v_mul_f32_e32 v91, 0xbfb8aa3b, v78
	v_cndmask_b32_e64 v92, v92, v84, s[8:9]
	v_cndmask_b32_e64 v93, v93, v85, s[8:9]
	v_add_f32_e32 v90, 1.0, v90
	v_rcp_f32_e32 v90, v90
	v_exp_f32_e32 v91, v91
	v_cndmask_b32_e64 v158, v103, v165, s[6:7]
	v_cndmask_b32_e64 v159, v139, v167, s[6:7]
	v_pk_mul_f32 v[150:151], v[126:127], v[150:151]
	v_pk_mul_f32 v[92:93], v[120:121], v[92:93]
	v_cndmask_b32_e64 v88, v80, v88, s[6:7]
	v_cndmask_b32_e64 v89, v81, v89, s[6:7]
	v_pk_fma_f32 v[150:151], v[130:131], v[158:159], v[150:151]
	v_pk_fma_f32 v[88:89], v[112:113], v[88:89], v[92:93]
	s_waitcnt vmcnt(0)
	v_pk_fma_f32 v[74:75], v[74:75], v[134:135], v[150:151]
	v_pk_fma_f32 v[76:77], v[76:77], v[116:117], v[88:89]
	v_mul_f32_e32 v79, v79, v90
	v_mul_f32_e32 v75, v79, v75
	v_add_f32_e32 v79, 1.0, v91
	v_mul_f32_e32 v88, 0xbfb8aa3b, v77
	v_mul_f32_e32 v89, 0xbfb8aa3b, v76
	v_rcp_f32_e32 v79, v79
	v_exp_f32_e32 v88, v88
	v_exp_f32_e32 v89, v89
	v_cndmask_b32_e64 v142, v164, v102, s[8:9]
	v_mul_f32_e32 v78, v78, v79
	v_add_f32_e32 v79, 1.0, v88
	v_add_f32_e32 v88, 1.0, v89
	v_rcp_f32_e32 v79, v79
	v_rcp_f32_e32 v88, v88
	v_cndmask_b32_e64 v143, v166, v138, s[8:9]
	v_cndmask_b32_e64 v156, v100, v162, s[6:7]
	v_cndmask_b32_e64 v157, v101, v163, s[6:7]
	v_pk_mul_f32 v[142:143], v[124:125], v[142:143]
	v_mul_f32_e32 v77, v77, v79
	v_pk_fma_f32 v[142:143], v[128:129], v[156:157], v[142:143]
	v_mul_f32_e32 v76, v76, v88
	v_pk_fma_f32 v[72:73], v[72:73], v[132:133], v[142:143]
	v_mul_f32_e32 v74, v78, v74
	v_mul_f32_e32 v73, v77, v73
	v_mul_f32_e32 v72, v76, v72
	v_cvt_pk_bf16_f32 v72, v72, v73
	v_cvt_pk_bf16_f32 v73, v74, v75
	v_mov_b64_e32 v[74:75], s[30:31]
	v_mad_i64_i32 v[74:75], s[70:71], v136, s67, v[74:75]
	v_lshl_add_u64 v[74:75], v[192:193], 1, v[74:75]
	global_store_dwordx2 v[74:75], v[72:73], off
.LBB0_706:
	s_or_b64 exec, exec, s[28:29]
	v_mov_b32_e32 v72, 0
	v_mov_b32_e32 v76, 0
	v_mov_b32_e32 v73, 0
	v_mov_b32_e32 v77, 0
	v_mov_b32_e32 v74, 0
	v_mov_b32_e32 v78, 0
	v_mov_b32_e32 v75, 0
	v_mov_b32_e32 v79, 0
	v_mov_b32_e32 v88, 0
	v_mov_b32_e32 v90, 0
	v_mov_b32_e32 v89, 0
	v_mov_b32_e32 v92, 0
	v_mov_b32_e32 v91, 0
	v_mov_b32_e32 v94, 0
	v_mov_b32_e32 v93, 0
	v_mov_b32_e32 v95, 0
	v_mov_b32_dpp v72, v96 row_ror:1 row_mask:0xf bank_mask:0xf
	v_mov_b32_dpp v76, v96 row_ror:2 row_mask:0xf bank_mask:0xf
	v_mov_b32_dpp v73, v97 row_ror:1 row_mask:0xf bank_mask:0xf
	v_mov_b32_dpp v77, v97 row_ror:2 row_mask:0xf bank_mask:0xf
	v_mov_b32_dpp v74, v98 row_ror:1 row_mask:0xf bank_mask:0xf
	v_mov_b32_dpp v78, v98 row_ror:2 row_mask:0xf bank_mask:0xf
	v_mov_b32_dpp v75, v99 row_ror:1 row_mask:0xf bank_mask:0xf
	v_mov_b32_dpp v79, v99 row_ror:2 row_mask:0xf bank_mask:0xf
	v_mov_b32_dpp v88, v104 row_ror:1 row_mask:0xf bank_mask:0xf
	v_mov_b32_dpp v90, v104 row_ror:2 row_mask:0xf bank_mask:0xf
	v_mov_b32_dpp v89, v105 row_ror:1 row_mask:0xf bank_mask:0xf
	v_mov_b32_dpp v92, v105 row_ror:2 row_mask:0xf bank_mask:0xf
	v_mov_b32_dpp v91, v106 row_ror:1 row_mask:0xf bank_mask:0xf
	v_mov_b32_dpp v94, v106 row_ror:2 row_mask:0xf bank_mask:0xf
	v_mov_b32_dpp v93, v107 row_ror:1 row_mask:0xf bank_mask:0xf
	v_mov_b32_dpp v95, v107 row_ror:2 row_mask:0xf bank_mask:0xf
	v_add_u32_e32 v210, 0xb0, v200
	v_cmp_le_u32_e64 s[28:29], s46, v210
	v_add_u32_e32 v137, s41, v210
	s_and_saveexec_b64 s[46:47], s[28:29]
	s_cbranch_execz .LBB0_708
	v_cndmask_b32_e64 v78, v86, v78, s[8:9]
	v_cndmask_b32_e64 v79, v87, v79, s[8:9]
	s_waitcnt vmcnt(5)
	v_pk_mul_f32 v[78:79], v[122:123], v[78:79]
	v_cndmask_b32_e64 v74, v74, v82, s[6:7]
	v_cndmask_b32_e64 v75, v75, v83, s[6:7]
	s_waitcnt vmcnt(3)
	v_pk_fma_f32 v[74:75], v[114:115], v[74:75], v[78:79]
	v_cndmask_b32_e64 v76, v84, v76, s[8:9]
	s_waitcnt vmcnt(1)
	v_pk_fma_f32 v[74:75], v[98:99], v[118:119], v[74:75]
	v_cndmask_b32_e64 v77, v85, v77, s[8:9]
	v_mul_f32_e32 v78, 0xbfb8aa3b, v75
	v_exp_f32_e32 v78, v78
	v_pk_mul_f32 v[76:77], v[120:121], v[76:77]
	v_cndmask_b32_e64 v72, v72, v80, s[6:7]
	v_cndmask_b32_e64 v73, v73, v81, s[6:7]
	v_pk_fma_f32 v[72:73], v[112:113], v[72:73], v[76:77]
	v_add_f32_e32 v76, 1.0, v78
	v_mul_f32_e32 v77, 0xbfb8aa3b, v74
	v_rcp_f32_e32 v76, v76
	v_exp_f32_e32 v77, v77
	v_pk_fma_f32 v[72:73], v[96:97], v[116:117], v[72:73]
	v_cndmask_b32_e64 v142, v102, v90, s[8:9]
	v_mul_f32_e32 v75, v75, v76
	v_add_f32_e32 v76, 1.0, v77
	v_mul_f32_e32 v77, 0xbfb8aa3b, v73
	v_mul_f32_e32 v78, 0xbfb8aa3b, v72
	v_rcp_f32_e32 v76, v76
	v_exp_f32_e32 v77, v77
	v_exp_f32_e32 v78, v78
	v_cndmask_b32_e64 v143, v138, v92, s[8:9]
	v_mul_f32_e32 v74, v74, v76
	v_add_f32_e32 v76, 1.0, v77
	v_add_f32_e32 v77, 1.0, v78
	v_rcp_f32_e32 v76, v76
	v_rcp_f32_e32 v77, v77
	v_cndmask_b32_e64 v94, v140, v94, s[8:9]
	v_cndmask_b32_e64 v95, v141, v95, s[8:9]
	v_cndmask_b32_e64 v88, v88, v100, s[6:7]
	v_cndmask_b32_e64 v89, v89, v101, s[6:7]
	v_cndmask_b32_e64 v90, v91, v103, s[6:7]
	v_cndmask_b32_e64 v91, v93, v139, s[6:7]
	v_pk_mul_f32 v[92:93], v[124:125], v[142:143]
	v_pk_mul_f32 v[94:95], v[126:127], v[94:95]
	v_pk_fma_f32 v[88:89], v[128:129], v[88:89], v[92:93]
	v_pk_fma_f32 v[90:91], v[130:131], v[90:91], v[94:95]
	s_waitcnt vmcnt(0)
	v_pk_fma_f32 v[88:89], v[104:105], v[132:133], v[88:89]
	v_pk_fma_f32 v[90:91], v[106:107], v[134:135], v[90:91]
	v_mul_f32_e32 v73, v73, v76
	v_mul_f32_e32 v72, v72, v77
	v_mul_f32_e32 v75, v75, v91
	v_mul_f32_e32 v74, v74, v90
	v_mul_f32_e32 v73, v73, v89
	v_mul_f32_e32 v72, v72, v88
	v_cvt_pk_bf16_f32 v72, v72, v73
	v_cvt_pk_bf16_f32 v73, v74, v75
	v_mov_b64_e32 v[74:75], s[30:31]
	v_mad_i64_i32 v[74:75], s[70:71], v137, s67, v[74:75]
	v_lshl_add_u64 v[74:75], v[192:193], 1, v[74:75]
	global_store_dwordx2 v[74:75], v[72:73], off
